# W_out transposes moved from P4's idle tail to P1's idle tail (P4 tail empty; W_q stays at the end of P5)
# speedup vs baseline: 1.0011x; 1.0011x over previous
.LBB0_136:
	s_cmp_lt_u32 s2, 0x128
	s_cbranch_scc1 .Lta_done
	s_cmp_ge_u32 s2, 0x1e0
	s_cbranch_scc1 .Lta_done
	s_load_dwordx2 s[30:31], s[0:1], 0x40
	s_load_dwordx2 s[32:33], s[0:1], 0xb0
	s_load_dwordx2 s[34:35], s[0:1], 0xc8
	s_load_dwordx2 s[36:37], s[0:1], 0xd0
	s_load_dwordx2 s[38:39], s[0:1], 0xe0
	s_movk_i32 s3, 184
	v_lshrrev_b32_e32 v0, 4, v204
	v_and_b32_e32 v1, 15, v204
	v_lshlrev_b32_e32 v1, 4, v1
	v_lshrrev_b32_e32 v2, 3, v204
	v_and_b32_e32 v3, 7, v204
	v_add_u32_e32 v8, 0, v0
	v_mul_u32_u24_e32 v8, 0x104, v8
	v_add3_u32 v8, v8, v1, 32
	v_add_u32_e32 v72, 0x4100, v8
	v_add_u32_e32 v9, 16, v0
	v_mul_u32_u24_e32 v9, 0x104, v9
	v_add3_u32 v9, v9, v1, 32
	v_add_u32_e32 v73, 0x4100, v9
	v_add_u32_e32 v10, 32, v0
	v_mul_u32_u24_e32 v10, 0x104, v10
	v_add3_u32 v10, v10, v1, 32
	v_add_u32_e32 v74, 0x4100, v10
	v_add_u32_e32 v11, 48, v0
	v_mul_u32_u24_e32 v11, 0x104, v11
	v_add3_u32 v11, v11, v1, 32
	v_add_u32_e32 v75, 0x4100, v11
	v_mul_u32_u24_e32 v12, 0x820, v3
	v_lshl_add_u32 v12, v2, 2, v12
	v_add_u32_e32 v12, 32, v12
	v_add_u32_e32 v13, 0x410, v12
	v_add_u32_e32 v76, 0x4100, v12
	v_add_u32_e32 v77, 0x4100, v13
	v_lshlrev_b32_e32 v14, 12, v2
	v_lshl_add_u32 v14, v3, 4, v14
	v_add_u32_e32 v78, 0, v0
	v_add_u32_e32 v79, 16, v0
	v_add_u32_e32 v80, 32, v0
	v_add_u32_e32 v81, 48, v0
	s_waitcnt lgkmcnt(0)
	s_sub_u32 s4, s2, 0x128
	s_add_u32 s4, s4, 0x1700
	s_cmpk_ge_u32 s4, 0x1f00
	s_cbranch_scc1 .Lta_done
	s_mov_b32 s5, s4
